# grid barrier: the per-CU L1 invalidate (buffer_inv sc1) is issued at arrival, before polling, so its latency overlaps the wait (this CU issues no plain load until the barrier completes)
# baseline (speedup 1.0000x reference)
; __device__ __forceinline__ unsigned xb_ld(unsigned* p)              { return __hip_atomic_load(p, __ATOMIC_RELAXED, __HIP_MEMORY_SCOPE_AGENT); }
; __device__ __forceinline__ unsigned xb_add(unsigned* p, unsigned v) { return __hip_atomic_fetch_add(p, v, __ATOMIC_RELAXED, __HIP_MEMORY_SCOPE_AGENT); }
; #define XB_SPIN(cond, bar) do { unsigned _sp = 0; while (cond) { __builtin_amdgcn_s_sleep(1); \
;     if ((++_sp & 255u) == 0u) { if (xb_ld(&(bar)[XB_TMO])) break; if (_sp > XB_SPIN_CAP) { atomicAdd(&(bar)[XB_TMO], 1u); break; } } } } while (0)
; __device__ __forceinline__ void xcd_barrier(const XcdBarrier& b) {
;     ...
;             else XB_SPIN(xb_ld(&bar[XB_TOPGEN]) == tg, bar);
;             __builtin_amdgcn_fence(__ATOMIC_ACQUIRE, "agent");
;             xb_add(&bar[XB_XGEN(b.x)], 1u);
;             asm volatile("s_waitcnt vmcnt(0)" ::: "memory");
;         } else {
;             XB_SPIN(xb_ld(&bar[XB_XGEN(b.x)]) == gen, bar);
;             __builtin_amdgcn_fence(__ATOMIC_ACQUIRE, "agent");
;             asm volatile("s_waitcnt vmcnt(0)" ::: "memory");
;         }
.Lgb_poll:
	buffer_inv sc1
	s_mov_b32 s9, 0
.Lgb_spin:
	global_load_dword v1, v3, s[6:7] sc1
	s_waitcnt vmcnt(0)
	v_readfirstlane_b32 s10, v1
	s_sub_i32 s10, s10, s8
	s_cmp_ge_i32 s10, 0
	s_cbranch_scc1 .Lgb_done
	s_sleep 1
	s_add_u32 s9, s9, 1
	s_cmp_lt_u32 s9, 0x8000
	s_cbranch_scc1 .Lgb_spin
.Lgb_done:
	s_waitcnt vmcnt(0)
.LBB0_604:
	s_or_b64 exec, exec, s[0:1]
	s_mov_b64 s[0:1], 0
	s_waitcnt lgkmcnt(0)
	s_barrier
